# gla_state item: chunk-state output goes through a wave-private padded LDS transpose and two 16-byte global stores per lane instead of 16 scattered 2-byte stores; otherwise as v42
# baseline (speedup 1.0000x reference)
; __device__ __forceinline__ unsigned f2bf(float f) { unsigned u = __float_as_uint(f); return (u + 0x7fffu + ((u >> 16) & 1u)) >> 16; }
; __device__ __forceinline__ void gla_state_item(unsigned char* lds, unsigned char* ws, const float* wgate, const float* bgate, int l, int item) {
;     ...
;     const bf16_t* Vt = (const bf16_t*)(lds + GL_VT);
;     f32x4 acc[4];
; #pragma unroll
;     for (int cb = 0; cb < 4; ++cb) acc[cb] = (f32x4){0.f, 0.f, 0.f, 0.f};
; #pragma unroll
;     for (int kk = 0; kk < 2; ++kk) {
;         const bf16x8 a = *(const bf16x8*)(Vt + (wid * 16 + ql) * 72 + kk * 32 + g * 8);
; #pragma unroll
;         for (int cb = 0; cb < 4; ++cb) { const bf16x8 bb = *(const bf16x8*)(KDt + (cb * 16 + ql) * 72 + kk * 32 + g * 8); acc[cb] = __builtin_amdgcn_mfma_f32_16x16x32_bf16(a, bb, acc[cb], 0, 0, 0); }
;     }
;     bf16_t* st = (bf16_t*)(ws + O_ST) + (size_t)item * 8192;
; #pragma unroll
;     for (int cb = 0; cb < 4; ++cb)
; #pragma unroll
;         for (int j = 0; j < 4; ++j) st[(wid * 16 + g * 4 + j) * 64 + cb * 16 + ql] = (bf16_t)f2bf(acc[cb][j]);
;     __syncthreads();
.LBB0_669:
	s_or_b64 exec, exec, s[0:1]
	v_and_b32_e32 v7, 15, v4
	v_and_b32_e32 v3, 48, v9
	v_lshl_or_b32 v2, v10, 4, v7
	v_add_u32_e32 v6, 0, v3
	v_mad_u64_u32 v[24:25], s[0:1], v2, s76, v[6:7]
	s_waitcnt lgkmcnt(0)
	s_barrier
	ds_read_b128 v[2:5], v24 offset:46336
	v_mad_u32_u24 v28, v7, s76, v6
	v_lshlrev_b32_e32 v6, 4, v9
	v_lshlrev_b32_e32 v8, 10, v10
	s_movk_i32 s0, 0x300
	v_and_or_b32 v6, v6, s0, v8
	ds_read_b128 v[12:15], v28 offset:27904
	ds_read_b128 v[16:19], v28 offset:30208
	ds_read_b128 v[20:23], v28 offset:32512
	v_ashrrev_i32_e32 v29, 31, v6
	v_or_b32_e32 v30, v7, v6
	ds_read_b128 v[6:9], v28 offset:34816
	s_waitcnt lgkmcnt(3)
	v_mfma_f32_16x16x32_bf16 v[12:15], v[2:5], v[12:15], 0
	v_lshlrev_b64 v[0:1], 14, v[0:1]
	v_lshl_add_u64 v[0:1], s[20:21], 0, v[0:1]
	v_ashrrev_i32_e32 v31, 31, v30
	s_waitcnt lgkmcnt(2)
	v_mfma_f32_16x16x32_bf16 v[16:19], v[2:5], v[16:19], 0
	s_add_i32 s10, s10, s97
	s_add_i32 s30, s30, s31
	s_cmpk_gt_i32 s10, 0x83f
	s_waitcnt lgkmcnt(1)
	v_mfma_f32_16x16x32_bf16 v[20:23], v[2:5], v[20:23], 0
	s_waitcnt lgkmcnt(0)
	v_mfma_f32_16x16x32_bf16 v[2:5], v[2:5], v[6:9], 0
	ds_read_b128 v[6:9], v24 offset:46400
	ds_read_b128 v[24:27], v28 offset:27968
	s_waitcnt lgkmcnt(0)
	v_mfma_f32_16x16x32_bf16 v[10:13], v[6:9], v[24:27], v[12:15]
	ds_read_b128 v[24:27], v28 offset:30272
	s_waitcnt lgkmcnt(0)
	v_mfma_f32_16x16x32_bf16 v[14:17], v[6:9], v[24:27], v[16:19]
	ds_read_b128 v[24:27], v28 offset:32576
	s_waitcnt lgkmcnt(0)
	v_mfma_f32_16x16x32_bf16 v[18:21], v[6:9], v[24:27], v[20:23]
	s_nop 2
	ds_read_b128 v[22:25], v28 offset:34880
	v_or_b32_e32 v28, 16, v30
	s_waitcnt lgkmcnt(0)
	v_mfma_f32_16x16x32_bf16 v[2:5], v[6:9], v[22:25], v[2:5]
	v_lshrrev_b32_e32 v26, 6, v203
	v_bfe_u32 v27, v203, 4, 2
	v_mul_u32_u24_e32 v26, 0x880, v26
	v_mul_u32_u24_e32 v27, 0x220, v27
	v_and_b32_e32 v28, 15, v203
	v_add3_u32 v27, v26, v27, 0
	v_lshl_add_u32 v26, v28, 1, v27
	v_bfe_u32 v6, v10, 16, 1
	v_add3_u32 v6, v10, v6, s86
	ds_write_b16_d16_hi v26, v6 offset:64768
	v_bfe_u32 v8, v11, 16, 1
	v_add3_u32 v8, v11, v8, s86
	ds_write_b16_d16_hi v26, v8 offset:64896
	v_bfe_u32 v6, v12, 16, 1
	v_add3_u32 v6, v12, v6, s86
	ds_write_b16_d16_hi v26, v6 offset:65024
	v_bfe_u32 v8, v13, 16, 1
	v_add3_u32 v8, v13, v8, s86
	ds_write_b16_d16_hi v26, v8 offset:65152
	v_bfe_u32 v6, v14, 16, 1
	v_add3_u32 v6, v14, v6, s86
	ds_write_b16_d16_hi v26, v6 offset:64800
	v_bfe_u32 v8, v15, 16, 1
	v_add3_u32 v8, v15, v8, s86
	ds_write_b16_d16_hi v26, v8 offset:64928
	v_bfe_u32 v6, v16, 16, 1
	v_add3_u32 v6, v16, v6, s86
	ds_write_b16_d16_hi v26, v6 offset:65056
	v_bfe_u32 v8, v17, 16, 1
	v_add3_u32 v8, v17, v8, s86
	ds_write_b16_d16_hi v26, v8 offset:65184
	v_bfe_u32 v6, v18, 16, 1
	v_add3_u32 v6, v18, v6, s86
	ds_write_b16_d16_hi v26, v6 offset:64832
	v_bfe_u32 v8, v19, 16, 1
	v_add3_u32 v8, v19, v8, s86
	ds_write_b16_d16_hi v26, v8 offset:64960
	v_bfe_u32 v6, v20, 16, 1
	v_add3_u32 v6, v20, v6, s86
	ds_write_b16_d16_hi v26, v6 offset:65088
	v_bfe_u32 v8, v21, 16, 1
	v_add3_u32 v8, v21, v8, s86
	ds_write_b16_d16_hi v26, v8 offset:65216
	v_bfe_u32 v6, v2, 16, 1
	v_add3_u32 v6, v2, v6, s86
	ds_write_b16_d16_hi v26, v6 offset:64864
	v_bfe_u32 v8, v3, 16, 1
	v_add3_u32 v8, v3, v8, s86
	ds_write_b16_d16_hi v26, v8 offset:64992
	v_bfe_u32 v6, v4, 16, 1
	v_add3_u32 v6, v4, v6, s86
	ds_write_b16_d16_hi v26, v6 offset:65120
	v_bfe_u32 v8, v5, 16, 1
	v_add3_u32 v8, v5, v8, s86
	ds_write_b16_d16_hi v26, v8 offset:65248
	v_lshl_add_u32 v27, v28, 5, v27
	v_lshlrev_b32_e32 v28, 5, v203
	v_mov_b32_e32 v29, 0
	s_waitcnt lgkmcnt(0)
	ds_read_b128 v[6:9], v27 offset:64768
	ds_read_b128 v[22:25], v27 offset:64784
	v_lshl_add_u64 v[28:29], v[28:29], 0, v[0:1]
	s_waitcnt lgkmcnt(0)
	global_store_dwordx4 v[28:29], v[6:9], off
	global_store_dwordx4 v[28:29], v[22:25], off offset:16
	s_barrier
	s_cbranch_scc1 .LBB0_726
